# top-k threshold search: 7-candidate loop unrolled, per-candidate exec toggle and lane-0 LDS write replaced by v_writelane + one ds_write per step
# speedup vs baseline: 1.0187x; 1.0102x over previous
.LBB0_611:
	s_mul_i32 s6, s28, -3
	s_add_i32 s8, s6, 28
	s_cmp_lg_u32 s28, 10
	v_cndmask_b32_e64 v10, 0, 1, s[20:21]
	s_cselect_b64 s[24:25], -1, 0
	v_lshlrev_b32_e32 v10, 8, v10
	s_and_b64 s[6:7], s[24:25], exec
	v_add_u32_e32 v10, s45, v10
	s_cselect_b32 s29, s8, 0
	s_waitcnt vmcnt(0)
	s_lshl_b32 s6, 1, s29
	s_or_b32 s26, s6, s38
	v_cmp_le_u32_e64 s[16:17], s26, v6
	v_cmp_le_u32_e64 s[18:19], s26, v7
	v_cmp_le_u32_e64 s[14:15], s26, v8
	v_cmp_le_u32_e64 s[12:13], s26, v9
	v_cmp_le_u32_e64 s[10:11], s26, v2
	v_cmp_le_u32_e64 s[8:9], s26, v3
	v_cmp_le_u32_e64 s[6:7], s26, v4
	v_cmp_le_u32_e32 vcc, s26, v5
	s_bcnt1_i32_b64 s16, s[16:17]
	s_bcnt1_i32_b64 s17, s[18:19]
	s_add_i32 s16, s17, s16
	s_bcnt1_i32_b64 s14, s[14:15]
	s_add_i32 s14, s16, s14
	s_bcnt1_i32_b64 s12, s[12:13]
	s_add_i32 s12, s14, s12
	s_bcnt1_i32_b64 s10, s[10:11]
	s_add_i32 s10, s12, s10
	s_bcnt1_i32_b64 s8, s[8:9]
	s_add_i32 s8, s10, s8
	s_bcnt1_i32_b64 s6, s[6:7]
	s_add_i32 s6, s8, s6
	s_bcnt1_i32_b64 s7, vcc
	s_add_i32 s6, s6, s7
	v_writelane_b32 v11, s6, 0
	s_cmp_eq_u64 s[24:25], 0
	s_cbranch_scc1 .Ltk_w5
	s_lshl_b32 s6, 2, s29
	s_or_b32 s26, s6, s38
	v_cmp_le_u32_e64 s[16:17], s26, v6
	v_cmp_le_u32_e64 s[18:19], s26, v7
	v_cmp_le_u32_e64 s[14:15], s26, v8
	v_cmp_le_u32_e64 s[12:13], s26, v9
	v_cmp_le_u32_e64 s[10:11], s26, v2
	v_cmp_le_u32_e64 s[8:9], s26, v3
	v_cmp_le_u32_e64 s[6:7], s26, v4
	v_cmp_le_u32_e32 vcc, s26, v5
	s_bcnt1_i32_b64 s16, s[16:17]
	s_bcnt1_i32_b64 s17, s[18:19]
	s_add_i32 s16, s17, s16
	s_bcnt1_i32_b64 s14, s[14:15]
	s_add_i32 s14, s16, s14
	s_bcnt1_i32_b64 s12, s[12:13]
	s_add_i32 s12, s14, s12
	s_bcnt1_i32_b64 s10, s[10:11]
	s_add_i32 s10, s12, s10
	s_bcnt1_i32_b64 s8, s[8:9]
	s_add_i32 s8, s10, s8
	s_bcnt1_i32_b64 s6, s[6:7]
	s_add_i32 s6, s8, s6
	s_bcnt1_i32_b64 s7, vcc
	s_add_i32 s6, s6, s7
	v_writelane_b32 v11, s6, 1
	s_lshl_b32 s6, 3, s29
	s_or_b32 s26, s6, s38
	v_cmp_le_u32_e64 s[16:17], s26, v6
	v_cmp_le_u32_e64 s[18:19], s26, v7
	v_cmp_le_u32_e64 s[14:15], s26, v8
	v_cmp_le_u32_e64 s[12:13], s26, v9
	v_cmp_le_u32_e64 s[10:11], s26, v2
	v_cmp_le_u32_e64 s[8:9], s26, v3
	v_cmp_le_u32_e64 s[6:7], s26, v4
	v_cmp_le_u32_e32 vcc, s26, v5
	s_bcnt1_i32_b64 s16, s[16:17]
	s_bcnt1_i32_b64 s17, s[18:19]
	s_add_i32 s16, s17, s16
	s_bcnt1_i32_b64 s14, s[14:15]
	s_add_i32 s14, s16, s14
	s_bcnt1_i32_b64 s12, s[12:13]
	s_add_i32 s12, s14, s12
	s_bcnt1_i32_b64 s10, s[10:11]
	s_add_i32 s10, s12, s10
	s_bcnt1_i32_b64 s8, s[8:9]
	s_add_i32 s8, s10, s8
	s_bcnt1_i32_b64 s6, s[6:7]
	s_add_i32 s6, s8, s6
	s_bcnt1_i32_b64 s7, vcc
	s_add_i32 s6, s6, s7
	v_writelane_b32 v11, s6, 2
	s_lshl_b32 s6, 4, s29
	s_or_b32 s26, s6, s38
	v_cmp_le_u32_e64 s[16:17], s26, v6
	v_cmp_le_u32_e64 s[18:19], s26, v7
	v_cmp_le_u32_e64 s[14:15], s26, v8
	v_cmp_le_u32_e64 s[12:13], s26, v9
	v_cmp_le_u32_e64 s[10:11], s26, v2
	v_cmp_le_u32_e64 s[8:9], s26, v3
	v_cmp_le_u32_e64 s[6:7], s26, v4
	v_cmp_le_u32_e32 vcc, s26, v5
	s_bcnt1_i32_b64 s16, s[16:17]
	s_bcnt1_i32_b64 s17, s[18:19]
	s_add_i32 s16, s17, s16
	s_bcnt1_i32_b64 s14, s[14:15]
	s_add_i32 s14, s16, s14
	s_bcnt1_i32_b64 s12, s[12:13]
	s_add_i32 s12, s14, s12
	s_bcnt1_i32_b64 s10, s[10:11]
	s_add_i32 s10, s12, s10
	s_bcnt1_i32_b64 s8, s[8:9]
	s_add_i32 s8, s10, s8
	s_bcnt1_i32_b64 s6, s[6:7]
	s_add_i32 s6, s8, s6
	s_bcnt1_i32_b64 s7, vcc
	s_add_i32 s6, s6, s7
	v_writelane_b32 v11, s6, 3
	s_lshl_b32 s6, 5, s29
	s_or_b32 s26, s6, s38
	v_cmp_le_u32_e64 s[16:17], s26, v6
	v_cmp_le_u32_e64 s[18:19], s26, v7
	v_cmp_le_u32_e64 s[14:15], s26, v8
	v_cmp_le_u32_e64 s[12:13], s26, v9
	v_cmp_le_u32_e64 s[10:11], s26, v2
	v_cmp_le_u32_e64 s[8:9], s26, v3
	v_cmp_le_u32_e64 s[6:7], s26, v4
	v_cmp_le_u32_e32 vcc, s26, v5
	s_bcnt1_i32_b64 s16, s[16:17]
	s_bcnt1_i32_b64 s17, s[18:19]
	s_add_i32 s16, s17, s16
	s_bcnt1_i32_b64 s14, s[14:15]
	s_add_i32 s14, s16, s14
	s_bcnt1_i32_b64 s12, s[12:13]
	s_add_i32 s12, s14, s12
	s_bcnt1_i32_b64 s10, s[10:11]
	s_add_i32 s10, s12, s10
	s_bcnt1_i32_b64 s8, s[8:9]
	s_add_i32 s8, s10, s8
	s_bcnt1_i32_b64 s6, s[6:7]
	s_add_i32 s6, s8, s6
	s_bcnt1_i32_b64 s7, vcc
	s_add_i32 s6, s6, s7
	v_writelane_b32 v11, s6, 4
	s_lshl_b32 s6, 6, s29
	s_or_b32 s26, s6, s38
	v_cmp_le_u32_e64 s[16:17], s26, v6
	v_cmp_le_u32_e64 s[18:19], s26, v7
	v_cmp_le_u32_e64 s[14:15], s26, v8
	v_cmp_le_u32_e64 s[12:13], s26, v9
	v_cmp_le_u32_e64 s[10:11], s26, v2
	v_cmp_le_u32_e64 s[8:9], s26, v3
	v_cmp_le_u32_e64 s[6:7], s26, v4
	v_cmp_le_u32_e32 vcc, s26, v5
	s_bcnt1_i32_b64 s16, s[16:17]
	s_bcnt1_i32_b64 s17, s[18:19]
	s_add_i32 s16, s17, s16
	s_bcnt1_i32_b64 s14, s[14:15]
	s_add_i32 s14, s16, s14
	s_bcnt1_i32_b64 s12, s[12:13]
	s_add_i32 s12, s14, s12
	s_bcnt1_i32_b64 s10, s[10:11]
	s_add_i32 s10, s12, s10
	s_bcnt1_i32_b64 s8, s[8:9]
	s_add_i32 s8, s10, s8
	s_bcnt1_i32_b64 s6, s[6:7]
	s_add_i32 s6, s8, s6
	s_bcnt1_i32_b64 s7, vcc
	s_add_i32 s6, s6, s7
	v_writelane_b32 v11, s6, 5
	s_lshl_b32 s6, 7, s29
	s_or_b32 s26, s6, s38
	v_cmp_le_u32_e64 s[16:17], s26, v6
	v_cmp_le_u32_e64 s[18:19], s26, v7
	v_cmp_le_u32_e64 s[14:15], s26, v8
	v_cmp_le_u32_e64 s[12:13], s26, v9
	v_cmp_le_u32_e64 s[10:11], s26, v2
	v_cmp_le_u32_e64 s[8:9], s26, v3
	v_cmp_le_u32_e64 s[6:7], s26, v4
	v_cmp_le_u32_e32 vcc, s26, v5
	s_bcnt1_i32_b64 s16, s[16:17]
	s_bcnt1_i32_b64 s17, s[18:19]
	s_add_i32 s16, s17, s16
	s_bcnt1_i32_b64 s14, s[14:15]
	s_add_i32 s14, s16, s14
	s_bcnt1_i32_b64 s12, s[12:13]
	s_add_i32 s12, s14, s12
	s_bcnt1_i32_b64 s10, s[10:11]
	s_add_i32 s10, s12, s10
	s_bcnt1_i32_b64 s8, s[8:9]
	s_add_i32 s8, s10, s8
	s_bcnt1_i32_b64 s6, s[6:7]
	s_add_i32 s6, s8, s6
	s_bcnt1_i32_b64 s7, vcc
	s_add_i32 s6, s6, s7
	v_writelane_b32 v11, s6, 6
.Ltk_w5:
	v_lshl_add_u32 v10, v47, 2, v10
	s_mov_b64 s[26:27], exec
	s_mov_b64 exec, 0x7f
	ds_write_b32 v10, v11
	s_mov_b64 exec, s[26:27]
